# attention: half-tile start stagger for co-resident block (HW wave-slot parity), 25x64 cycles
# baseline (speedup 1.0000x reference)
; __device__ __forceinline__ void ph_attn(const P& p, int need_ctx, char* smem) {
;     ...
;   const int tid = (threadIdx.x + zz), lane = tid & 63, wave = tid >> 6, lr = lane & 15, lq = lane >> 4;
;   int ntask = 8 * 4 * 16 + (need_ctx ? 8 * 4 * 2 : 0);
;   for (int task = (blockIdx.x + zz); task < ntask; task += (gridDim.x + zz)) {
;     int b, h, qrow0, nkt;
;     if (task < 512) { b = task >> 6; h = (task >> 4) & 3; int qt = task & 15; qrow0 = b * 2048 + qt * 128; nkt = 36; }
;     else { int t2 = task - 512; b = t2 >> 3; h = (t2 >> 1) & 3; int qt = t2 & 1; qrow0 = T_LAT + b * 256 + qt * 128; nkt = 4; }
;     bf16x8 qf[2][3];
; #pragma unroll
;     for (int qs = 0; qs < 2; qs++) {
;       const u16* qp = QB + (size_t)(qrow0 + wave * 32 + qs * 16 + lr) * 384 + h * 96 + lq * 8;
; #pragma unroll
;       for (int ks = 0; ks < 3; ks++) qf[qs][ks] = *(const bf16x8*)(qp + ks * 32);
;     }
;     f32x4 o[2][4];
;     float m[2], lsum[2];
; #pragma unroll
;     for (int qs = 0; qs < 2; qs++) {
;       m[qs] = -1e30f; lsum[qs] = 0.f;
; #pragma unroll
;       for (int i = 0; i < 4; i++) o[qs][i] = (f32x4){0.f, 0.f, 0.f, 0.f};
;     }
;     u32x4 rk[3], rv[2];
;     ...
;     ATT_LOAD(0);
.LBB0_1239:
	s_or_b64 exec, exec, s[6:7]
	s_and_b64 s[0:1], s[40:41], exec
	s_movk_i32 s0, 0x240
	s_mov_b32 s20, 0
	s_cselect_b32 s16, 0x200, s0
	s_add_i32 s17, s20, s87
	v_mov_b32_e32 v196, 0x80
	s_cmp_ge_i32 s17, s16
	s_cbranch_scc1 .LBB0_1262
	s_getreg_b32 s0, hwreg(HW_REG_HW_ID, 0, 4)
	s_and_b32 s0, s0, 1
	s_cmp_eq_u32 s0, 0
	s_cbranch_scc1 .Latt_nostg
	s_sleep 25
.Latt_nostg:
	s_ashr_i32 s1, s20, 31
	v_add_u32_e32 v0, s20, v128
	s_waitcnt lgkmcnt(0)
	s_add_u32 s0, s2, s20
	v_and_b32_e32 v1, 15, v0
	v_bfe_u32 v2, v0, 4, 2
	v_ashrrev_i32_e32 v3, 1, v0
	s_movk_i32 s4, 0xffe0
	s_addc_u32 s1, s3, s1
	s_waitcnt vmcnt(0)
	v_and_or_b32 v95, v3, s4, v1
	v_lshlrev_b32_e32 v132, 3, v2
	v_lshlrev_b32_e32 v2, 4, v2
	v_mov_b32_e32 v3, v133
	v_lshl_add_u64 v[4:5], s[0:1], 0, v[2:3]
	s_mov_b64 s[4:5], 0x1e319000
	v_lshlrev_b32_e32 v3, 4, v0
	v_lshl_add_u64 v[76:77], v[4:5], 0, s[4:5]
	v_and_b32_e32 v4, 0x70, v3
	v_mov_b32_e32 v5, v133
	v_lshl_add_u64 v[6:7], s[0:1], 0, v[4:5]
	v_and_b32_e32 v5, 64, v212
	v_xor_b32_e32 v3, 16, v212
	v_add_u32_e32 v5, 64, v5
	v_cmp_lt_i32_e32 vcc, v3, v5
	s_mov_b64 s[4:5], 0x1f999000
	s_mov_b32 s8, 0x2aaaaaab
	v_cndmask_b32_e32 v3, v212, v3, vcc
	v_lshlrev_b32_e32 v97, 2, v3
	v_xor_b32_e32 v3, 32, v212
	v_lshl_add_u64 v[78:79], v[6:7], 0, s[4:5]
	v_cmp_lt_i32_e32 vcc, v3, v5
	v_lshl_add_u64 v[6:7], s[0:1], 0, v[132:133]
	s_mov_b64 s[4:5], 0x12f19000
	v_mul_hi_i32 v5, v0, s8
	v_lshl_add_u64 v[80:81], v[6:7], 0, s[4:5]
	v_lshrrev_b32_e32 v6, 31, v5
	v_ashrrev_i32_e32 v5, 1, v5
	v_add_u32_e32 v118, v5, v6
	v_add_u32_e32 v8, 0x100, v0
	v_mad_u64_u32 v[6:7], s[4:5], v118, -12, v[0:1]
	v_mul_hi_i32 v5, v8, s8
	v_lshrrev_b32_e32 v7, 31, v5
	v_ashrrev_i32_e32 v5, 1, v5
	v_add_u32_e32 v12, 0x200, v0
	s_add_u32 s18, s0, 0x1f099000
	v_add_u32_e32 v119, v5, v7
	v_mul_hi_i32 v5, v12, s8
	s_addc_u32 s19, s1, 0
	v_lshrrev_b32_e32 v7, 31, v5
	v_ashrrev_i32_e32 v5, 1, v5
	s_add_u32 s2, s0, 0x20299000
	v_cndmask_b32_e32 v3, v212, v3, vcc
	v_lshlrev_b32_e32 v82, 3, v6
	v_mad_u64_u32 v[10:11], s[6:7], v119, -12, v[8:9]
	v_add_u32_e32 v120, v5, v7
	s_addc_u32 s3, s1, 0
	v_lshlrev_b32_e32 v99, 2, v3
	v_sub_u32_e32 v3, v2, v132
	v_subrev_u32_e32 v132, 64, v82
	v_lshlrev_b32_e32 v86, 3, v10
	v_mad_u64_u32 v[12:13], s[8:9], v120, -12, v[12:13]
	v_lshl_add_u64 v[84:85], v[132:133], 1, s[2:3]
	v_subrev_u32_e32 v132, 64, v86
	v_lshlrev_b32_e32 v90, 3, v12
	v_lshl_add_u64 v[88:89], v[132:133], 1, s[2:3]
	v_subrev_u32_e32 v132, 64, v90
	v_ashrrev_i32_e32 v121, 3, v0
	v_and_b32_e32 v0, 7, v0
	v_lshl_add_u64 v[92:93], v[132:133], 1, s[2:3]
	v_ashrrev_i32_e32 v122, 3, v8
	v_mul_u32_u24_e32 v5, 0x90, v1
	s_movk_i32 s2, 0xd0
	v_mul_u32_u24_e32 v17, 0xd0, v1
	v_or_b32_e32 v1, 16, v1
	v_lshlrev_b32_e32 v132, 4, v0
	v_mul_lo_u32 v7, v118, s2
	v_lshlrev_b32_e32 v8, 4, v6
	v_mul_lo_u32 v9, v119, s2
	v_lshlrev_b32_e32 v11, 4, v10
	v_mul_lo_u32 v13, v120, s2
	v_lshlrev_b32_e32 v14, 4, v12
	v_mul_lo_u32 v15, v121, s33
	v_mul_lo_u32 v16, v122, s33
	v_mul_u32_u24_e32 v18, 0x90, v1
	v_cmp_gt_i32_e64 s[10:11], 8, v6
	v_cmp_gt_i32_e64 s[12:13], 8, v10
	v_cmp_gt_i32_e64 s[14:15], 8, v12
	v_lshl_add_u64 v[0:1], s[0:1], 0, v[132:133]
	s_mov_b64 s[0:1], 0x1f999080
	s_add_i32 s20, s20, s90
	v_cmp_lt_i32_e64 s[4:5], 7, v6
	v_ashrrev_i32_e32 v83, 31, v82
	v_cmp_lt_i32_e64 s[6:7], 7, v10
	v_ashrrev_i32_e32 v87, 31, v86
	v_cmp_lt_i32_e64 s[8:9], 7, v12
	v_ashrrev_i32_e32 v91, 31, v90
	v_cndmask_b32_e64 v94, 6, 9, s[10:11]
	v_cndmask_b32_e64 v96, 6, 9, s[12:13]
	v_cndmask_b32_e64 v98, 6, 9, s[14:15]
	v_lshl_add_u64 v[100:101], v[0:1], 0, s[0:1]
	v_add_u32_e32 v123, v7, v8
	v_add_u32_e32 v124, v9, v11
	v_add_u32_e32 v125, v13, v14
	v_add_u32_e32 v126, v4, v15
	v_add_u32_e32 v127, v4, v16
	v_add_u32_e32 v129, v2, v17
	v_add_u32_e32 v131, v3, v5
	v_add_u32_e32 v132, v3, v18
	s_branch .LBB0_1242
